# stack16: SSD output unit issues its 20 tile-fill global loads together behind counted waits instead of one vmcnt(0) round trip per load (on top of stack15)
# speedup vs baseline: 1.0093x; 1.0093x over previous
; DI float bf2f(unsigned h) { return __uint_as_float(h << 16); }
; DI unsigned pk2(float lo, float hi) { return pg8::cvt_pk_bf16(lo, hi); }
; DI unsigned short f2bf(float f) { return (unsigned short)(pg8::cvt_pk_bf16(f, 0.f) & 0xffffu); }
; DI void ssd_out_unit(const Params& P, int layer, int b, int c, char* lds, int tid) {
;     ...
; #pragma unroll
;         for (int i = 0; i < 4; ++i) { const int q = tid + 512 * i, l = q >> 4, n0 = (q & 15) * 8;
;             *(u32x4*)(BM + l * SP + n0) = *(const u32x4*)(SSDB + (size_t)(R0 + l) * 768 + 256 + 128 * g + n0);
;             *(u32x4*)(CM + l * SP + n0) = *(const u32x4*)(SSDB + (size_t)(R0 + l) * 768 + 512 + 128 * g + n0); }
; #pragma unroll
;         for (int hs = 0; hs < 2; ++hs) { const int h = 2 * g + hs;
; #pragma unroll
;             for (int i = 0; i < 2; ++i) { const int q = tid + 512 * i, l = q & 127, p0 = (q >> 7) * 8;
;                 const u32x4 v = *(const u32x4*)(SSDB + (size_t)(R0 + l) * 768 + 64 * h + p0); const float f = dtl[h * CH + l];
;                 bf16_t* d = XT[hs] + p0 * SP + l;
;                 d[0] = f2bf(bf2f(v.x & 0xffffu) * f); d[SP] = f2bf(bf2f(v.x >> 16) * f); d[2 * SP] = f2bf(bf2f(v.y & 0xffffu) * f); d[3 * SP] = f2bf(bf2f(v.y >> 16) * f);
;                 d[4 * SP] = f2bf(bf2f(v.z & 0xffffu) * f); d[5 * SP] = f2bf(bf2f(v.z >> 16) * f); d[6 * SP] = f2bf(bf2f(v.w & 0xffffu) * f); d[7 * SP] = f2bf(bf2f(v.w >> 16) * f); }
;             const float* sp = ST + ((size_t)((b * NCHUNK + c) * 4 + h)) * 8192;
; #pragma unroll
;             for (int i = 0; i < 4; ++i) { const int q = tid + 512 * i, p = q >> 5, n0 = (q & 31) * 4; const f32x4 v = *(const f32x4*)(sp + p * 128 + n0);
;                 u32x2 w; w.x = pk2(v.x, v.y); w.y = pk2(v.z, v.w); *(u32x2*)(PV[hs] + p * SP + n0) = w; } }
.LBB0_369:
	s_lshl_b32 s62, s5, 8
	s_lshl_b32 s13, s5, 10
	s_lshl_b32 s16, s5, 1
	s_or_b32 s22, s16, s4
	s_ashr_i32 s23, s22, 31
	s_lshl_b64 s[22:23], s[22:23], 15
	s_or_b32 s16, s16, 1
	s_waitcnt lgkmcnt(0)
	s_barrier
	v_add_u32_e32 v191, s13, v148
	ds_read_b32 v236, v191
	v_lshl_add_u32 v191, s16, 9, v148
	ds_read_b32 v237, v191
	v_lshl_add_u64 v[2:3], v[96:97], 0, s[62:63]
	global_load_dwordx4 v[6:9], v[2:3], off offset:1024
	global_load_dwordx4 v[2:5], v[2:3], off offset:512
	v_lshl_add_u64 v[10:11], v[98:99], 0, s[62:63]
	global_load_dwordx4 v[14:17], v[10:11], off offset:1024
	global_load_dwordx4 v[10:13], v[10:11], off offset:512
	v_lshl_add_u64 v[18:19], v[100:101], 0, s[62:63]
	global_load_dwordx4 v[22:25], v[18:19], off offset:1024
	global_load_dwordx4 v[18:21], v[18:19], off offset:512
	v_lshl_add_u64 v[26:27], v[102:103], 0, s[62:63]
	global_load_dwordx4 v[30:33], v[26:27], off offset:1024
	global_load_dwordx4 v[26:29], v[26:27], off offset:512
	v_lshl_add_u64 v[216:217], v[92:93], 0, s[62:63]
	v_lshl_add_u64 v[34:35], v[216:217], 0, v[80:81]
	global_load_dwordx4 v[34:37], v[34:35], off
	v_lshl_add_u64 v[38:39], v[216:217], 0, v[82:83]
	global_load_dwordx4 v[38:41], v[38:39], off
	v_lshl_add_u64 v[216:217], v[54:55], 0, s[22:23]
	v_lshl_add_u64 v[42:43], v[216:217], 0, v[84:85]
	global_load_dwordx4 v[42:45], v[42:43], off
	v_lshl_add_u64 v[46:47], v[216:217], 0, v[86:87]
	global_load_dwordx4 v[46:49], v[46:47], off
	v_lshl_add_u64 v[220:221], v[216:217], 0, v[88:89]
	global_load_dwordx4 v[220:223], v[220:221], off
	v_lshl_add_u64 v[224:225], v[216:217], 0, v[90:91]
	global_load_dwordx4 v[224:227], v[224:225], off
	s_lshl_b32 s62, s16, 7
	v_lshl_add_u64 v[216:217], v[92:93], 0, s[62:63]
	v_lshl_add_u64 v[228:229], v[216:217], 0, v[80:81]
	global_load_dwordx4 v[228:231], v[228:229], off
	v_lshl_add_u64 v[232:233], v[216:217], 0, v[82:83]
	global_load_dwordx4 v[232:235], v[232:233], off
	s_or_b32 s22, s16, s4
	s_ashr_i32 s23, s22, 31
	s_lshl_b64 s[22:23], s[22:23], 15
	v_lshl_add_u64 v[216:217], v[54:55], 0, s[22:23]
	v_lshl_add_u64 v[244:245], v[216:217], 0, v[84:85]
	global_load_dwordx4 v[244:247], v[244:245], off
	v_lshl_add_u64 v[248:249], v[216:217], 0, v[86:87]
	global_load_dwordx4 v[248:251], v[248:249], off
	v_lshl_add_u64 v[252:253], v[216:217], 0, v[88:89]
	global_load_dwordx4 v[252:255], v[252:253], off
	v_lshl_add_u64 v[216:217], v[216:217], 0, v[90:91]
	global_load_dwordx4 v[216:219], v[216:217], off
	s_add_i32 s16, s13, 0
	s_add_i32 s16, s16, 0x22020
	v_lshl_add_u32 v174, v154, 2, s16
	s_waitcnt vmcnt(19)
	ds_write_b128 v58, v[6:9]
	s_waitcnt vmcnt(18)
	ds_write_b128 v58, v[2:5] offset:34816
	s_waitcnt vmcnt(17)
	ds_write_b128 v60, v[14:17]
	s_waitcnt vmcnt(16)
	ds_write_b128 v60, v[10:13] offset:34816
	s_waitcnt vmcnt(15)
	ds_write_b128 v62, v[22:25]
	s_waitcnt vmcnt(14)
	ds_write_b128 v62, v[18:21] offset:34816
	s_waitcnt vmcnt(13)
	ds_write_b128 v64, v[30:33]
	s_waitcnt vmcnt(12)
	ds_write_b128 v64, v[26:29] offset:34816
	s_waitcnt vmcnt(11)
	s_waitcnt lgkmcnt(0)
	v_lshlrev_b32_e32 v190, 16, v34
	v_mul_f32_e32 v190, v236, v190
	v_cvt_pk_bf16_f32 v190, v190, v1
	ds_write_b16 v65, v190
	v_and_b32_e32 v190, 0xffff0000, v34
	v_mul_f32_e32 v190, v236, v190
	v_cvt_pk_bf16_f32 v190, v190, v1
	ds_write_b16 v65, v190 offset:272
	v_lshlrev_b32_e32 v190, 16, v35
	v_mul_f32_e32 v190, v236, v190
	v_cvt_pk_bf16_f32 v190, v190, v1
	ds_write_b16 v65, v190 offset:544
	v_and_b32_e32 v190, 0xffff0000, v35
	v_mul_f32_e32 v190, v236, v190
	v_cvt_pk_bf16_f32 v190, v190, v1
	ds_write_b16 v65, v190 offset:816
	v_lshlrev_b32_e32 v190, 16, v36
	v_mul_f32_e32 v190, v236, v190
	v_cvt_pk_bf16_f32 v190, v190, v1
	ds_write_b16 v65, v190 offset:1088
	v_and_b32_e32 v190, 0xffff0000, v36
	v_mul_f32_e32 v190, v236, v190
	v_cvt_pk_bf16_f32 v190, v190, v1
	ds_write_b16 v65, v190 offset:1360
	v_lshlrev_b32_e32 v190, 16, v37
	v_mul_f32_e32 v190, v236, v190
	v_cvt_pk_bf16_f32 v190, v190, v1
	ds_write_b16 v65, v190 offset:1632
	v_and_b32_e32 v190, 0xffff0000, v37
	v_mul_f32_e32 v190, v236, v190
	v_cvt_pk_bf16_f32 v190, v190, v1
	ds_write_b16 v65, v190 offset:1904
	s_waitcnt vmcnt(10)
	v_lshlrev_b32_e32 v190, 16, v38
	v_mul_f32_e32 v190, v236, v190
	v_cvt_pk_bf16_f32 v190, v190, v1
	ds_write_b16 v156, v190
	v_and_b32_e32 v190, 0xffff0000, v38
	v_mul_f32_e32 v190, v236, v190
	v_cvt_pk_bf16_f32 v190, v190, v1
	ds_write_b16 v156, v190 offset:272
	v_lshlrev_b32_e32 v190, 16, v39
	v_mul_f32_e32 v190, v236, v190
	v_cvt_pk_bf16_f32 v190, v190, v1
	ds_write_b16 v156, v190 offset:544
	v_and_b32_e32 v190, 0xffff0000, v39
	v_mul_f32_e32 v190, v236, v190
	v_cvt_pk_bf16_f32 v190, v190, v1
	ds_write_b16 v156, v190 offset:816
	v_lshlrev_b32_e32 v190, 16, v40
	v_mul_f32_e32 v190, v236, v190
	v_cvt_pk_bf16_f32 v190, v190, v1
	ds_write_b16 v156, v190 offset:1088
	v_and_b32_e32 v190, 0xffff0000, v40
	v_mul_f32_e32 v190, v236, v190
	v_cvt_pk_bf16_f32 v190, v190, v1
	ds_write_b16 v156, v190 offset:1360
	v_lshlrev_b32_e32 v190, 16, v41
	v_mul_f32_e32 v190, v236, v190
	v_cvt_pk_bf16_f32 v190, v190, v1
	ds_write_b16 v156, v190 offset:1632
	v_and_b32_e32 v190, 0xffff0000, v41
	v_mul_f32_e32 v190, v236, v190
	v_cvt_pk_bf16_f32 v190, v190, v1
	ds_write_b16 v156, v190 offset:1904
	s_waitcnt vmcnt(9)
	v_cvt_pk_bf16_f32 v42, v42, v43
	v_cvt_pk_bf16_f32 v43, v44, v45
	ds_write_b64 v157, v[42:43]
	s_waitcnt vmcnt(8)
	v_cvt_pk_bf16_f32 v46, v46, v47
	v_cvt_pk_bf16_f32 v47, v48, v49
	ds_write_b64 v158, v[46:47]
	s_waitcnt vmcnt(7)
	v_cvt_pk_bf16_f32 v220, v220, v221
	v_cvt_pk_bf16_f32 v221, v222, v223
	ds_write_b64 v159, v[220:221]
	s_waitcnt vmcnt(6)
; DI float bf2f(unsigned h) { return __uint_as_float(h << 16); }
; DI unsigned pk2(float lo, float hi) { return pg8::cvt_pk_bf16(lo, hi); }
; DI unsigned short f2bf(float f) { return (unsigned short)(pg8::cvt_pk_bf16(f, 0.f) & 0xffffu); }
; DI void ssd_out_unit(const Params& P, int layer, int b, int c, char* lds, int tid) {
;     ...
; #pragma unroll
;         for (int hs = 0; hs < 2; ++hs) { const int h = 2 * g + hs;
; #pragma unroll
;             for (int i = 0; i < 2; ++i) { const int q = tid + 512 * i, l = q & 127, p0 = (q >> 7) * 8;
;                 const u32x4 v = *(const u32x4*)(SSDB + (size_t)(R0 + l) * 768 + 64 * h + p0); const float f = dtl[h * CH + l];
;                 bf16_t* d = XT[hs] + p0 * SP + l;
;                 d[0] = f2bf(bf2f(v.x & 0xffffu) * f); d[SP] = f2bf(bf2f(v.x >> 16) * f); d[2 * SP] = f2bf(bf2f(v.y & 0xffffu) * f); d[3 * SP] = f2bf(bf2f(v.y >> 16) * f);
;                 d[4 * SP] = f2bf(bf2f(v.z & 0xffffu) * f); d[5 * SP] = f2bf(bf2f(v.z >> 16) * f); d[6 * SP] = f2bf(bf2f(v.w & 0xffffu) * f); d[7 * SP] = f2bf(bf2f(v.w >> 16) * f); }
;             const float* sp = ST + ((size_t)((b * NCHUNK + c) * 4 + h)) * 8192;
; #pragma unroll
;             for (int i = 0; i < 4; ++i) { const int q = tid + 512 * i, p = q >> 5, n0 = (q & 31) * 4; const f32x4 v = *(const f32x4*)(sp + p * 128 + n0);
;                 u32x2 w; w.x = pk2(v.x, v.y); w.y = pk2(v.z, v.w); *(u32x2*)(PV[hs] + p * SP + n0) = w; } }
;         __syncthreads();
	v_cvt_pk_bf16_f32 v224, v224, v225
	v_cvt_pk_bf16_f32 v225, v226, v227
	ds_write_b64 v160, v[224:225]
	s_waitcnt vmcnt(5)
	v_lshlrev_b32_e32 v190, 16, v228
	v_mul_f32_e32 v190, v237, v190
	v_cvt_pk_bf16_f32 v190, v190, v1
	ds_write_b16 v161, v190
	v_and_b32_e32 v190, 0xffff0000, v228
	v_mul_f32_e32 v190, v237, v190
	v_cvt_pk_bf16_f32 v190, v190, v1
	ds_write_b16 v161, v190 offset:272
	v_lshlrev_b32_e32 v190, 16, v229
	v_mul_f32_e32 v190, v237, v190
	v_cvt_pk_bf16_f32 v190, v190, v1
	ds_write_b16 v161, v190 offset:544
	v_and_b32_e32 v190, 0xffff0000, v229
	v_mul_f32_e32 v190, v237, v190
	v_cvt_pk_bf16_f32 v190, v190, v1
	ds_write_b16 v161, v190 offset:816
	v_lshlrev_b32_e32 v190, 16, v230
	v_mul_f32_e32 v190, v237, v190
	v_cvt_pk_bf16_f32 v190, v190, v1
	ds_write_b16 v161, v190 offset:1088
	v_and_b32_e32 v190, 0xffff0000, v230
	v_mul_f32_e32 v190, v237, v190
	v_cvt_pk_bf16_f32 v190, v190, v1
	ds_write_b16 v161, v190 offset:1360
	v_lshlrev_b32_e32 v190, 16, v231
	v_mul_f32_e32 v190, v237, v190
	v_cvt_pk_bf16_f32 v190, v190, v1
	ds_write_b16 v161, v190 offset:1632
	v_and_b32_e32 v190, 0xffff0000, v231
	v_mul_f32_e32 v190, v237, v190
	v_cvt_pk_bf16_f32 v190, v190, v1
	ds_write_b16 v161, v190 offset:1904
	s_waitcnt vmcnt(4)
	v_lshlrev_b32_e32 v190, 16, v232
	v_mul_f32_e32 v190, v237, v190
	v_cvt_pk_bf16_f32 v190, v190, v1
	ds_write_b16 v162, v190
	v_and_b32_e32 v190, 0xffff0000, v232
	v_mul_f32_e32 v190, v237, v190
	v_cvt_pk_bf16_f32 v190, v190, v1
	ds_write_b16 v162, v190 offset:272
	v_lshlrev_b32_e32 v190, 16, v233
	v_mul_f32_e32 v190, v237, v190
	v_cvt_pk_bf16_f32 v190, v190, v1
	ds_write_b16 v162, v190 offset:544
	v_and_b32_e32 v190, 0xffff0000, v233
	v_mul_f32_e32 v190, v237, v190
	v_cvt_pk_bf16_f32 v190, v190, v1
	ds_write_b16 v162, v190 offset:816
	v_lshlrev_b32_e32 v190, 16, v234
	v_mul_f32_e32 v190, v237, v190
	v_cvt_pk_bf16_f32 v190, v190, v1
	ds_write_b16 v162, v190 offset:1088
	v_and_b32_e32 v190, 0xffff0000, v234
	v_mul_f32_e32 v190, v237, v190
	v_cvt_pk_bf16_f32 v190, v190, v1
	ds_write_b16 v162, v190 offset:1360
	v_lshlrev_b32_e32 v190, 16, v235
	v_mul_f32_e32 v190, v237, v190
	v_cvt_pk_bf16_f32 v190, v190, v1
	ds_write_b16 v162, v190 offset:1632
	v_and_b32_e32 v190, 0xffff0000, v235
	v_mul_f32_e32 v190, v237, v190
	v_cvt_pk_bf16_f32 v190, v190, v1
	ds_write_b16 v162, v190 offset:1904
	s_waitcnt vmcnt(3)
	v_cvt_pk_bf16_f32 v244, v244, v245
	v_cvt_pk_bf16_f32 v245, v246, v247
	ds_write_b64 v163, v[244:245]
	s_waitcnt vmcnt(2)
	v_cvt_pk_bf16_f32 v248, v248, v249
	v_cvt_pk_bf16_f32 v249, v250, v251
	ds_write_b64 v164, v[248:249]
	s_waitcnt vmcnt(1)
	v_cvt_pk_bf16_f32 v252, v252, v253
	v_cvt_pk_bf16_f32 v253, v254, v255
	ds_write_b64 v165, v[252:253]
	s_waitcnt vmcnt(0)
	v_cvt_pk_bf16_f32 v216, v216, v217
	v_cvt_pk_bf16_f32 v217, v218, v219
	ds_write_b64 v166, v[216:217]
	s_waitcnt lgkmcnt(0)
	s_barrier
; DI int crow(int r, int h) { return (r & 3) + 8 * (r >> 2) + 4 * h; }
; #define MFMA32(a, b, c) __builtin_amdgcn_mfma_f32_32x32x16_bf16((a), (b), (c), 0, 0, 0)
; DI void ssd_out_unit(const Params& P, int layer, int b, int c, char* lds, int tid) {
;     ...
;         f32x16 y0 = {}, y1 = {};
; #pragma unroll
;         for (int ks = 0; ks < 8; ++ks) { const bf16x8 a = *(const bf16x8*)(CM + (32 * lb + r) * SP + 16 * ks + 8 * hh);
;             const bf16x8 b0 = *(const bf16x8*)(PV[0] + (32 * pb + r) * SP + 16 * ks + 8 * hh), b1 = *(const bf16x8*)(PV[1] + (32 * pb + r) * SP + 16 * ks + 8 * hh);
;             y0 = MFMA32(a, b0, y0); y1 = MFMA32(a, b1, y1); }
;         const float* ac0 = acs + (2 * g) * CH; const float* ac1 = ac0 + CH;
; #pragma unroll
;         for (int i = 0; i < 16; ++i) { const int l = 32 * lb + crow(i, hh); y0[i] *= __expf(ac0[l]); y1[i] *= __expf(ac1[l]); }
;         const float al0 = ac0[32 * lb + r], al1 = ac1[32 * lb + r];
;         for (int sbk = 0; sbk <= lb; ++sbk) {
	ds_read_b128 v[18:21], v151
	ds_read_b128 v[34:37], v151 offset:32
	ds_read_b128 v[2:5], v152
	ds_read_b128 v[38:41], v152 offset:32
	ds_read_b128 v[22:25], v153
	ds_read_b128 v[42:45], v153 offset:32
	s_waitcnt lgkmcnt(3)
	v_mfma_f32_32x32x16_bf16 v[2:17], v[18:21], v[2:5], 0
	s_waitcnt lgkmcnt(1)
	v_mfma_f32_32x32x16_bf16 v[18:33], v[18:21], v[22:25], 0
	v_mfma_f32_32x32x16_bf16 v[2:17], v[34:37], v[38:41], v[2:17]
	s_waitcnt lgkmcnt(0)
	v_mfma_f32_32x32x16_bf16 v[18:33], v[34:37], v[42:45], v[18:33]
	ds_read_b128 v[34:37], v151 offset:64
	ds_read_b128 v[38:41], v152 offset:64
	ds_read_b128 v[42:45], v153 offset:64
	s_waitcnt lgkmcnt(1)
	v_mfma_f32_32x32x16_bf16 v[2:17], v[34:37], v[38:41], v[2:17]
	s_waitcnt lgkmcnt(0)
	v_mfma_f32_32x32x16_bf16 v[18:33], v[34:37], v[42:45], v[18:33]
	ds_read_b128 v[34:37], v151 offset:96
	ds_read_b128 v[38:41], v152 offset:96
	ds_read_b128 v[42:45], v153 offset:96
	s_waitcnt lgkmcnt(1)
	v_mfma_f32_32x32x16_bf16 v[2:17], v[34:37], v[38:41], v[2:17]
	s_waitcnt lgkmcnt(0)
	v_mfma_f32_32x32x16_bf16 v[18:33], v[34:37], v[42:45], v[18:33]
	ds_read_b128 v[34:37], v151 offset:128
	ds_read_b128 v[38:41], v152 offset:128
	ds_read_b128 v[42:45], v153 offset:128
	s_waitcnt lgkmcnt(1)
	v_mfma_f32_32x32x16_bf16 v[2:17], v[34:37], v[38:41], v[2:17]
	s_waitcnt lgkmcnt(0)
	v_mfma_f32_32x32x16_bf16 v[18:33], v[34:37], v[42:45], v[18:33]
	ds_read_b128 v[34:37], v151 offset:160
	ds_read_b128 v[38:41], v152 offset:160
	ds_read_b128 v[42:45], v153 offset:160
	s_waitcnt lgkmcnt(1)
	v_mfma_f32_32x32x16_bf16 v[2:17], v[34:37], v[38:41], v[2:17]
	s_waitcnt lgkmcnt(0)
	v_mfma_f32_32x32x16_bf16 v[18:33], v[34:37], v[42:45], v[18:33]
	ds_read_b128 v[34:37], v151 offset:192
	ds_read_b128 v[38:41], v152 offset:192
	ds_read_b128 v[42:45], v153 offset:192
	s_waitcnt lgkmcnt(1)
	v_mfma_f32_32x32x16_bf16 v[2:17], v[34:37], v[38:41], v[2:17]
	s_waitcnt lgkmcnt(0)
	v_mfma_f32_32x32x16_bf16 v[18:33], v[34:37], v[42:45], v[18:33]
	ds_read_b128 v[34:37], v151 offset:224
	ds_read_b128 v[38:41], v152 offset:224
	ds_read_b128 v[42:45], v153 offset:224
	s_waitcnt lgkmcnt(1)
	v_mfma_f32_32x32x16_bf16 v[2:17], v[34:37], v[38:41], v[2:17]
	s_waitcnt lgkmcnt(0)
	v_mfma_f32_32x32x16_bf16 v[18:33], v[34:37], v[42:45], v[18:33]
	ds_read_b128 v[36:39], v174
	ds_read_b128 v[40:43], v174 offset:32
	ds_read_b128 v[134:137], v174 offset:512
	s_waitcnt lgkmcnt(2)
	v_mul_f32_e32 v34, 0x3fb8aa3b, v36
	v_exp_f32_e32 v46, v34
	s_waitcnt lgkmcnt(0)
	v_mul_f32_e32 v34, 0x3fb8aa3b, v134
	v_exp_f32_e32 v36, v34
	v_mul_f32_e32 v34, 0x3fb8aa3b, v37
	v_exp_f32_e32 v47, v34
	v_mul_f32_e32 v34, 0x3fb8aa3b, v135
	v_exp_f32_e32 v37, v34
	v_mul_f32_e32 v34, 0x3fb8aa3b, v38
	v_mul_f32_e32 v35, 0x3fb8aa3b, v39
	v_exp_f32_e32 v48, v34
	v_mul_f32_e32 v34, 0x3fb8aa3b, v136
	v_exp_f32_e32 v49, v35
	v_mul_f32_e32 v35, 0x3fb8aa3b, v137
	ds_read_b128 v[136:139], v174 offset:544
	v_mul_f32_e32 v38, 0x3fb8aa3b, v40
	v_mul_f32_e32 v39, 0x3fb8aa3b, v41
	v_mul_f32_e32 v40, 0x3fb8aa3b, v42
	v_mul_f32_e32 v41, 0x3fb8aa3b, v43
	ds_read_b128 v[42:45], v174 offset:64
	v_exp_f32_e32 v134, v38
	s_waitcnt lgkmcnt(1)
	v_mul_f32_e32 v38, 0x3fb8aa3b, v136
	v_exp_f32_e32 v135, v39
	v_mul_f32_e32 v39, 0x3fb8aa3b, v137
	v_exp_f32_e32 v136, v40
	v_mul_f32_e32 v40, 0x3fb8aa3b, v138
	v_exp_f32_e32 v137, v41
	v_mul_f32_e32 v41, 0x3fb8aa3b, v139
	ds_read_b128 v[138:141], v174 offset:576
	s_waitcnt lgkmcnt(1)
	v_mul_f32_e32 v42, 0x3fb8aa3b, v42
	v_mul_f32_e32 v43, 0x3fb8aa3b, v43
	v_mul_f32_e32 v44, 0x3fb8aa3b, v44
	v_mul_f32_e32 v45, 0x3fb8aa3b, v45
	v_exp_f32_e32 v142, v42
	s_waitcnt lgkmcnt(0)
	v_mul_f32_e32 v42, 0x3fb8aa3b, v138
	v_exp_f32_e32 v143, v43
	v_mul_f32_e32 v43, 0x3fb8aa3b, v139
	v_exp_f32_e32 v190, v44
	v_mul_f32_e32 v44, 0x3fb8aa3b, v140
	v_exp_f32_e32 v191, v45
	v_mul_f32_e32 v45, 0x3fb8aa3b, v141
	ds_read_b128 v[138:141], v174 offset:96
	ds_read_b128 v[174:177], v174 offset:608
	v_pk_mul_f32 v[2:3], v[2:3], v[46:47]
	v_exp_f32_e32 v34, v34
	v_exp_f32_e32 v35, v35
	s_waitcnt lgkmcnt(1)
	v_mul_f32_e32 v138, 0x3fb8aa3b, v138
	v_mul_f32_e32 v139, 0x3fb8aa3b, v139
	v_mul_f32_e32 v140, 0x3fb8aa3b, v140
	v_exp_f32_e32 v192, v138
	s_waitcnt lgkmcnt(0)
	v_mul_f32_e32 v138, 0x3fb8aa3b, v174
	v_exp_f32_e32 v193, v139
	v_mul_f32_e32 v139, 0x3fb8aa3b, v175
	v_exp_f32_e32 v174, v140
	v_mul_f32_e32 v140, 0x3fb8aa3b, v176
	v_mul_f32_e32 v141, 0x3fb8aa3b, v141
	v_mul_f32_e32 v46, 0x3fb8aa3b, v177
	v_exp_f32_e32 v38, v38
	v_exp_f32_e32 v39, v39
	v_exp_f32_e32 v40, v40
	v_exp_f32_e32 v41, v41
	v_exp_f32_e32 v42, v42
	v_exp_f32_e32 v43, v43
	v_exp_f32_e32 v44, v44
	v_exp_f32_e32 v45, v45
	v_exp_f32_e32 v138, v138
	v_exp_f32_e32 v139, v139
	v_exp_f32_e32 v140, v140
	v_exp_f32_e32 v175, v141
	v_exp_f32_e32 v141, v46
	v_pk_mul_f32 v[14:15], v[14:15], v[192:193]
	v_pk_mul_f32 v[12:13], v[12:13], v[190:191]
	v_pk_mul_f32 v[16:17], v[16:17], v[174:175]
	v_pk_mul_f32 v[10:11], v[10:11], v[142:143]
	v_pk_mul_f32 v[8:9], v[8:9], v[136:137]
	v_pk_mul_f32 v[6:7], v[6:7], v[134:135]
	v_pk_mul_f32 v[4:5], v[4:5], v[48:49]
	v_pk_mul_f32 v[18:19], v[18:19], v[36:37]
	v_pk_mul_f32 v[32:33], v[32:33], v[140:141]
	v_pk_mul_f32 v[30:31], v[30:31], v[138:139]
	v_pk_mul_f32 v[28:29], v[28:29], v[44:45]
	v_pk_mul_f32 v[26:27], v[26:27], v[42:43]
	v_pk_mul_f32 v[24:25], v[24:25], v[40:41]
	v_pk_mul_f32 v[22:23], v[22:23], v[38:39]
	v_pk_mul_f32 v[20:21], v[20:21], v[34:35]
	s_and_saveexec_b64 s[56:57], s[54:55]
	s_cbranch_execz .LBB0_368
	v_lshl_add_u32 v34, v149, 2, s16
	ds_read2st64_b32 v[134:135], v34 offset1:2
	v_add_u32_e32 v136, s13, v150
	s_mov_b64 s[58:59], 0
	v_mov_b32_e32 v137, v173
	v_mov_b32_e32 v138, v172
	v_mov_b32_e32 v139, v171
	v_mov_b32_e32 v140, v170
	s_branch .LBB0_372
